# baseline (speedup 1.0000x reference)
; __device__ __forceinline__ float bflo(unsigned w) { return __uint_as_float(w << 16); }
; __device__ __forceinline__ float bfhi(unsigned w) { return __uint_as_float(w & 0xffff0000u); }
; __device__ __forceinline__ int v_st(int k, int c) { const int kk = (k & ~0xC) | ((k & 4) << 1) | ((k & 8) >> 1); return ((kk >> 3) * 4 + (c >> 5)) * 512 + ((kk & 7) * 32 + (c & 31)) * 2; }
; __device__ __forceinline__ void load_q_roped(const bf16_t* Qw, const float* __restrict__ wq, const float* __restrict__ RT, int pr, int pc, int hi, int lane, bf16x8 (&qr)[8]) {
;   float y[8][8]; float ss = 0.f;
; #pragma unroll
;   for (int d0 = 0; d0 < 8; ++d0) { const u32x4 w = *(const u32x4*)(Qw + d0 * 16);
; #pragma unroll
;     for (int q = 0; q < 4; ++q) { y[d0][2 * q] = bflo(w[q]); y[d0][2 * q + 1] = bfhi(w[q]); } }
; #pragma unroll
;   for (int d0 = 0; d0 < 8; ++d0)
; #pragma unroll
;     for (int e = 0; e < 8; ++e) ss += y[d0][e] * y[d0][e];
; template <bool META>
; __device__ __forceinline__ void attn_unit(const bf16_t* Q, bf16_t* Oo, const bf16_t* __restrict__ Kb, const bf16_t* __restrict__ Vb, int b, int kvh, int h, int qb, char* lds, const int tid, const float* qn, const float* RT) {
;   constexpr int NT = 257, LDK = 256;
;   const int wid = tid >> 6, lane = tid & 63, r32 = lane & 31, hi = lane >> 5;
;   bf16_t* V_lds = (bf16_t*)lds; bf16_t* K_lds = (bf16_t*)(lds + 3 * SHM_V);
;   float* ws = (float*)(lds + 3 * SHM_V + 3 * SHM_K) + wid * 64; float* li_l = ws; float* al_l = ws + 32;
;   float m_reg = -1e30f, l_reg = 0; f32x16 o[4] = {}; bf16x8 qr[8];
;   const bf16_t* Kh = Kb + kvh * 128; const bf16_t* Vh = Vb + kvh * 128;
;   const long kv0 = (long)b * SEQ, mrow = NREAL + NMETA * b;
;   { const int sq = qb * 256 + wid * 32 + r32;
;     load_q_roped(Q + (size_t)(b * SEQ + sq) * 1024 + h * 128 + hi * 8, qn + hi * 8, RT, sq >> 6, sq & 63, hi, lane, qr); }
;   const int sr = tid >> 4, sc = (tid & 15) * 8, vst0 = v_st(sr, sc), vst1 = v_st(32 + sr, sc);
.LBB0_259:
	s_bfe_u32 s1, s2, 0x10008
	s_ashr_i32 s0, s2, 9
	s_lshl_b32 s3, s1, 8
	v_readlane_b32 s6, v255, 9
	v_readlane_b32 s7, v255, 10
	s_add_u32 s40, s6, s3
	s_addc_u32 s41, s7, 0
	v_readlane_b32 s6, v255, 5
	v_readlane_b32 s7, v255, 6
	s_add_u32 s42, s6, s3
	s_addc_u32 s43, s7, 0
	s_lshl_b32 s3, s2, 6
	s_and_b32 s3, s3, 0x3f00
	v_add_u32_e32 v191, s3, v172
	v_or_b32_e32 v21, v191, v163
	s_lshl_b32 s3, s0, 14
	v_add_u32_e32 v2, s3, v21
	s_lshl_b32 s4, s2, 7
	v_ashrrev_i32_e32 v3, 31, v2
	s_lshl_b32 s1, s1, 9
	s_and_b32 s4, s4, 0x180
	v_lshlrev_b64 v[2:3], 11, v[2:3]
	s_or_b32 s30, s1, s4
	v_lshl_add_u64 v[2:3], s[20:21], 0, v[2:3]
	s_lshl_b32 s4, s30, 1
	v_lshl_add_u64 v[2:3], v[2:3], 0, s[4:5]
	v_lshlrev_b32_e32 v0, 1, v162
	v_lshl_add_u64 v[18:19], v[2:3], 0, v[0:1]
	global_load_dwordx4 v[58:61], v[18:19], off offset:160
	global_load_dwordx4 v[62:65], v[18:19], off offset:224
	global_load_dwordx4 v[66:69], v[18:19], off offset:128
	global_load_dwordx4 v[70:73], v[18:19], off offset:192
	global_load_dwordx4 v[2:5], v[164:165], off
	global_load_dwordx4 v[6:9], v[164:165], off offset:16
	global_load_dwordx4 v[10:13], v[164:165], off offset:64
	global_load_dwordx4 v[82:85], v[164:165], off offset:80
	global_load_dwordx4 v[86:89], v[164:165], off offset:128
	global_load_dwordx4 v[90:93], v[164:165], off offset:144
	global_load_dwordx4 v[94:97], v[164:165], off offset:192
	global_load_dwordx4 v[98:101], v[164:165], off offset:208
	global_load_dwordx4 v[102:105], v[164:165], off offset:256
	global_load_dwordx4 v[106:109], v[164:165], off offset:272
	global_load_dwordx4 v[50:53], v[18:19], off offset:32
	global_load_dwordx4 v[110:113], v[164:165], off offset:320
	global_load_dwordx4 v[114:117], v[164:165], off offset:336
	global_load_dwordx4 v[54:57], v[18:19], off offset:96
	global_load_dwordx4 v[118:121], v[164:165], off offset:384
	global_load_dwordx4 v[122:125], v[164:165], off offset:400
	global_load_dwordx4 v[126:129], v[164:165], off offset:448
	global_load_dwordx4 v[14:17], v[164:165], off offset:464
	global_load_dwordx4 v[74:77], v[18:19], off
	s_lshl_b32 s4, s0, 4
	s_add_i32 s31, s4, 0x8000
	v_ashrrev_i32_e32 v0, 1, v191
	s_movk_i32 s4, 0xffe0
	v_and_or_b32 v20, v0, s4, v162
	v_lshlrev_b32_e32 v0, 5, v21
	v_ashrrev_i32_e32 v21, 31, v20
	v_or_b32_e32 v22, 16, v20
	v_lshl_add_u64 v[20:21], v[20:21], 3, s[48:49]
	global_load_dwordx4 v[78:81], v[18:19], off offset:64
	global_load_dwordx4 v[30:33], v[20:21], off offset:48
	global_load_dwordx4 v[38:41], v[20:21], off offset:32
	global_load_dwordx4 v[42:45], v[20:21], off offset:16
	global_load_dwordx4 v[46:49], v[20:21], off
	s_movk_i32 s4, 0x7e0
	v_and_or_b32 v0, v0, s4, v162
	v_lshlrev_b32_e32 v195, 3, v0
	v_mov_b32_e32 v196, v245
	v_mov_b64_e32 v[244:245], v[242:243]
	v_mov_b64_e32 v[174:175], v[248:249]
	v_ashrrev_i32_e32 v23, 31, v22
	v_lshl_add_u64 v[34:35], v[22:23], 3, s[48:49]
	global_load_dwordx4 v[18:21], v[34:35], off offset:48
	global_load_dwordx4 v[22:25], v[34:35], off offset:32
	global_load_dwordx4 v[26:29], v[34:35], off offset:16
	s_nop 0
	global_load_dwordx4 v[34:37], v[34:35], off
	s_ashr_i32 s1, s0, 31
	s_lshl_b64 s[90:91], s[0:1], 14
	s_ashr_i32 s44, s31, 31
	s_lshl_b64 s[0:1], s[0:1], 23
	s_add_u32 s6, s42, s0
	s_addc_u32 s7, s43, s1
	s_add_u32 s8, s40, s0
	s_addc_u32 s9, s41, s1
	s_mov_b32 s4, s5
	s_mov_b32 s10, s5
	s_mov_b32 s11, s5
	s_mov_b32 s12, s5
	s_mov_b32 s13, s5
	s_mov_b32 s14, s5
	s_mov_b32 s15, s5
	s_mov_b32 s16, s5
	s_mov_b32 s17, s5
	s_mov_b32 s18, s5
	s_mov_b32 s19, s5
	s_mov_b32 s28, 1
	s_waitcnt vmcnt(0)
	v_lshlrev_b32_e32 v142, 16, v58
	v_and_b32_e32 v143, 0xffff0000, v58
	v_lshlrev_b32_e32 v226, 16, v66
	v_and_b32_e32 v227, 0xffff0000, v66
	v_lshlrev_b32_e32 v218, 16, v67
	v_and_b32_e32 v219, 0xffff0000, v67
	v_pk_mul_f32 v[66:67], v[226:227], v[226:227]
	v_pk_mul_f32 v[222:223], v[218:219], v[218:219]
	v_lshlrev_b32_e32 v214, 16, v68
	v_and_b32_e32 v215, 0xffff0000, v68
	v_lshlrev_b32_e32 v144, 16, v69
	v_and_b32_e32 v145, 0xffff0000, v69
	v_pk_mul_f32 v[68:69], v[214:215], v[214:215]
	v_pk_mul_f32 v[210:211], v[144:145], v[144:145]
	v_lshlrev_b32_e32 v202, 16, v51
	v_and_b32_e32 v203, 0xffff0000, v51
	v_lshlrev_b32_e32 v150, 16, v50
	v_and_b32_e32 v151, 0xffff0000, v50
	v_lshlrev_b32_e32 v238, 16, v52
	v_and_b32_e32 v239, 0xffff0000, v52
	v_lshlrev_b32_e32 v230, 16, v53
	v_and_b32_e32 v231, 0xffff0000, v53
	v_lshlrev_b32_e32 v158, 16, v74
	v_and_b32_e32 v159, 0xffff0000, v74
	v_lshlrev_b32_e32 v156, 16, v75
	v_and_b32_e32 v157, 0xffff0000, v75
	v_pk_mul_f32 v[50:51], v[158:159], v[158:159]
	v_lshlrev_b32_e32 v154, 16, v76
	v_add_f32_e32 v0, v50, v51
	v_pk_mul_f32 v[50:51], v[156:157], v[156:157]
	v_and_b32_e32 v155, 0xffff0000, v76
	v_add_f32_e32 v0, v50, v0
	v_add_f32_e32 v0, v51, v0
	v_pk_mul_f32 v[50:51], v[154:155], v[154:155]
	v_lshlrev_b32_e32 v152, 16, v77
	v_and_b32_e32 v153, 0xffff0000, v77
	v_add_f32_e32 v0, v50, v0
	v_add_f32_e32 v0, v51, v0
	v_pk_mul_f32 v[50:51], v[152:153], v[152:153]
	v_pk_mul_f32 v[52:53], v[238:239], v[238:239]
	v_add_f32_e32 v0, v50, v0
	v_add_f32_e32 v0, v51, v0
	v_pk_mul_f32 v[50:51], v[150:151], v[150:151]
	v_pk_mul_f32 v[234:235], v[230:231], v[230:231]
	v_add_f32_e32 v0, v50, v0
	v_add_f32_e32 v0, v51, v0
	v_pk_mul_f32 v[50:51], v[202:203], v[202:203]
	v_lshlrev_b32_e32 v242, 16, v78
	v_add_f32_e32 v0, v50, v0
	v_add_f32_e32 v0, v51, v0
	v_add_f32_e32 v0, v52, v0
	v_add_f32_e32 v0, v53, v0
	v_and_b32_e32 v243, 0xffff0000, v78
	v_add_f32_e32 v0, v234, v0
	v_lshlrev_b32_e32 v198, 16, v55
	v_and_b32_e32 v199, 0xffff0000, v55
	v_lshlrev_b32_e32 v200, 16, v54
	v_and_b32_e32 v201, 0xffff0000, v54
; __device__ __forceinline__ float lane_read(float v, int src) { return __int_as_float(__builtin_amdgcn_ds_bpermute(src << 2, __float_as_int(v))); }
; __device__ __forceinline__ void load_q_roped(const bf16_t* Qw, const float* __restrict__ wq, const float* __restrict__ RT, int pr, int pc, int hi, int lane, bf16x8 (&qr)[8]) {
;     ...
;   ss += lane_read(ss, lane ^ 32);
;   const float rstd = __builtin_amdgcn_rsqf(ss * (1.f / 128.f) + 1e-6f);
; #pragma unroll
;   for (int d0 = 0; d0 < 8; ++d0) { const f32x4 w0 = *(const f32x4*)(wq + d0 * 16), w1 = *(const f32x4*)(wq + d0 * 16 + 4);
; #pragma unroll
;     for (int e = 0; e < 8; ++e) y[d0][e] *= rstd * (e < 4 ? w0[e & 3] : w1[e & 3]); }
; #pragma unroll
;   for (int hf = 0; hf < 2; ++hf)
; #pragma unroll
;     for (int lo = 0; lo < 2; ++lo) { const int d0 = hf * 4 + lo;
;       const float* tp = RT + (size_t)((hf ? pc : pr) * 32 + lo * 16 + hi * 8) * 2;
;       f32x4 t[4];
; #pragma unroll
;       for (int q = 0; q < 4; ++q) t[q] = *(const f32x4*)(tp + 4 * q);
; #pragma unroll
;       for (int e = 0; e < 8; ++e) { const float cs = t[e >> 1][(e & 1) * 2], sn = t[e >> 1][(e & 1) * 2 + 1];
;         const float x1 = y[d0][e], x2 = y[d0 + 2][e]; y[d0][e] = x1 * cs - x2 * sn; y[d0 + 2][e] = x1 * sn + x2 * cs; } }
	v_add_f32_e32 v0, v235, v0
	v_pk_mul_f32 v[54:55], v[242:243], v[242:243]
	v_lshlrev_b32_e32 v248, 16, v79
	v_and_b32_e32 v249, 0xffff0000, v79
	v_add_f32_e32 v0, v54, v0
	v_add_f32_e32 v0, v55, v0
	v_pk_mul_f32 v[54:55], v[248:249], v[248:249]
	v_lshlrev_b32_e32 v206, 16, v80
	v_and_b32_e32 v207, 0xffff0000, v80
	v_add_f32_e32 v0, v54, v0
	v_add_f32_e32 v0, v55, v0
	v_pk_mul_f32 v[54:55], v[206:207], v[206:207]
	v_lshlrev_b32_e32 v204, 16, v81
	v_and_b32_e32 v205, 0xffff0000, v81
	v_add_f32_e32 v0, v54, v0
	v_add_f32_e32 v0, v55, v0
	v_pk_mul_f32 v[54:55], v[204:205], v[204:205]
	v_pk_mul_f32 v[52:53], v[200:201], v[200:201]
	v_add_f32_e32 v0, v54, v0
	v_add_f32_e32 v0, v55, v0
	v_add_f32_e32 v0, v52, v0
	v_pk_mul_f32 v[50:51], v[198:199], v[198:199]
	v_add_f32_e32 v0, v53, v0
	v_lshlrev_b32_e32 v240, 16, v56
	v_and_b32_e32 v241, 0xffff0000, v56
	v_add_f32_e32 v0, v50, v0
	v_lshlrev_b32_e32 v232, 16, v57
	v_and_b32_e32 v233, 0xffff0000, v57
	v_pk_mul_f32 v[56:57], v[240:241], v[240:241]
	v_add_f32_e32 v0, v51, v0
	v_add_f32_e32 v0, v56, v0
	v_pk_mul_f32 v[236:237], v[232:233], v[232:233]
	v_add_f32_e32 v0, v57, v0
	v_add_f32_e32 v0, v236, v0
	v_add_f32_e32 v0, v237, v0
	v_add_f32_e32 v0, v66, v0
	v_add_f32_e32 v0, v67, v0
	v_add_f32_e32 v0, v222, v0
	v_add_f32_e32 v0, v223, v0
	v_add_f32_e32 v0, v68, v0
	v_add_f32_e32 v0, v69, v0
	v_add_f32_e32 v0, v210, v0
	v_pk_mul_f32 v[168:169], v[142:143], v[142:143]
	v_add_f32_e32 v0, v211, v0
	v_lshlrev_b32_e32 v138, 16, v59
	v_and_b32_e32 v139, 0xffff0000, v59
	v_add_f32_e32 v0, v168, v0
	v_pk_mul_f32 v[148:149], v[138:139], v[138:139]
	v_add_f32_e32 v0, v169, v0
	v_lshlrev_b32_e32 v136, 16, v60
	v_and_b32_e32 v137, 0xffff0000, v60
	v_add_f32_e32 v0, v148, v0
	v_lshlrev_b32_e32 v140, 16, v63
	v_and_b32_e32 v141, 0xffff0000, v63
	v_lshlrev_b32_e32 v146, 16, v62
	v_and_b32_e32 v147, 0xffff0000, v62
	v_pk_mul_f32 v[62:63], v[136:137], v[136:137]
	v_add_f32_e32 v0, v149, v0
	v_lshlrev_b32_e32 v134, 16, v61
	v_and_b32_e32 v135, 0xffff0000, v61
	v_add_f32_e32 v0, v62, v0
	v_pk_mul_f32 v[58:59], v[134:135], v[134:135]
	v_add_f32_e32 v0, v63, v0
	v_lshlrev_b32_e32 v228, 16, v70
	v_and_b32_e32 v229, 0xffff0000, v70
	v_add_f32_e32 v0, v58, v0
	v_lshlrev_b32_e32 v220, 16, v71
	v_and_b32_e32 v221, 0xffff0000, v71
	v_pk_mul_f32 v[70:71], v[228:229], v[228:229]
	v_add_f32_e32 v0, v59, v0
	v_add_f32_e32 v0, v70, v0
	v_pk_mul_f32 v[224:225], v[220:221], v[220:221]
	v_add_f32_e32 v0, v71, v0
	v_lshlrev_b32_e32 v216, 16, v72
	v_and_b32_e32 v217, 0xffff0000, v72
	v_add_f32_e32 v0, v224, v0
	v_lshlrev_b32_e32 v192, 16, v73
	v_and_b32_e32 v193, 0xffff0000, v73
	v_pk_mul_f32 v[72:73], v[216:217], v[216:217]
	v_add_f32_e32 v0, v225, v0
	v_add_f32_e32 v0, v72, v0
	v_pk_mul_f32 v[212:213], v[192:193], v[192:193]
	v_add_f32_e32 v0, v73, v0
	v_add_f32_e32 v0, v212, v0
	v_pk_mul_f32 v[170:171], v[146:147], v[146:147]
	v_add_f32_e32 v0, v213, v0
	v_add_f32_e32 v0, v170, v0
	v_pk_mul_f32 v[160:161], v[140:141], v[140:141]
	v_add_f32_e32 v0, v171, v0
	v_lshlrev_b32_e32 v132, 16, v64
	v_and_b32_e32 v133, 0xffff0000, v64
	v_add_f32_e32 v0, v160, v0
	v_lshlrev_b32_e32 v130, 16, v65
	v_and_b32_e32 v131, 0xffff0000, v65
	v_pk_mul_f32 v[64:65], v[132:133], v[132:133]
	v_add_f32_e32 v0, v161, v0
	v_add_f32_e32 v0, v64, v0
	v_pk_mul_f32 v[60:61], v[130:131], v[130:131]
	v_add_f32_e32 v0, v65, v0
	v_add_f32_e32 v0, v60, v0
	v_add_f32_e32 v0, v61, v0
	ds_bpermute_b32 v50, v252, v0
	global_load_dwordx4 v[66:69], v195, s[48:49] offset:48
	global_load_dwordx4 v[70:73], v195, s[48:49] offset:32
	global_load_dwordx4 v[74:77], v195, s[48:49] offset:16
	global_load_dwordx4 v[78:81], v195, s[48:49]
	v_add_u32_e32 v168, 0, v176
	v_add_u32_e32 v169, 0, v177
	v_lshl_add_u64 v[170:171], s[40:41], 0, v[166:167]
	s_waitcnt lgkmcnt(0)
	v_add_f32_e32 v0, v0, v50
	v_mov_b32_e32 v50, 0x358637bd
	v_fmamk_f32 v0, v0, 0x3c000000, v50
	v_rsq_f32_e32 v0, v0
	global_load_dwordx4 v[50:53], v195, s[48:49] offset:176
	global_load_dwordx4 v[54:57], v195, s[48:49] offset:160
	global_load_dwordx4 v[58:61], v195, s[48:49] offset:144
	global_load_dwordx4 v[62:65], v195, s[48:49] offset:128
	v_pk_mul_f32 v[14:15], v[14:15], v[0:1] op_sel_hi:[1,0]
	v_pk_mul_f32 v[126:127], v[126:127], v[0:1] op_sel_hi:[1,0]
	v_pk_mul_f32 v[116:117], v[116:117], v[0:1] op_sel_hi:[1,0]
	v_pk_mul_f32 v[86:87], v[86:87], v[0:1] op_sel_hi:[1,0]
	v_pk_mul_f32 v[14:15], v[14:15], v[132:133]
	v_pk_mul_f32 v[132:133], v[126:127], v[146:147]
	v_pk_mul_f32 v[126:127], v[116:117], v[134:135]
	v_pk_mul_f32 v[114:115], v[114:115], v[0:1] op_sel_hi:[1,0]
	v_pk_mul_f32 v[112:113], v[112:113], v[0:1] op_sel_hi:[1,0]
	v_pk_mul_f32 v[90:91], v[90:91], v[0:1] op_sel_hi:[1,0]
	v_pk_mul_f32 v[116:117], v[86:87], v[242:243]
	v_lshl_add_u64 v[86:87], s[6:7], 0, v[166:167]
	v_pk_mul_f32 v[134:135], v[114:115], v[136:137]
	v_pk_mul_f32 v[136:137], v[112:113], v[138:139]
	v_pk_mul_f32 v[110:111], v[110:111], v[0:1] op_sel_hi:[1,0]
	v_pk_mul_f32 v[108:109], v[108:109], v[0:1] op_sel_hi:[1,0]
	v_pk_mul_f32 v[106:107], v[106:107], v[0:1] op_sel_hi:[1,0]
	v_pk_mul_f32 v[112:113], v[90:91], v[206:207]
	v_add_co_u32_e32 v90, vcc, s37, v86
	v_pk_mul_f32 v[138:139], v[110:111], v[142:143]
	v_pk_mul_f32 v[142:143], v[108:109], v[144:145]
	v_pk_mul_f32 v[144:145], v[106:107], v[214:215]
	v_pk_mul_f32 v[104:105], v[104:105], v[0:1] op_sel_hi:[1,0]
	v_pk_mul_f32 v[102:103], v[102:103], v[0:1] op_sel_hi:[1,0]
	v_pk_mul_f32 v[92:93], v[92:93], v[0:1] op_sel_hi:[1,0]
	v_pk_mul_f32 v[88:89], v[88:89], v[0:1] op_sel_hi:[1,0]
	v_addc_co_u32_e32 v91, vcc, 0, v87, vcc
	v_lshl_add_u64 v[106:107], s[8:9], 0, v[184:185]
; __device__ __forceinline__ unsigned cvtpk(float lo, float hi) { const f32x2c v = {lo, hi}; const bf16x2c r = __builtin_convertvector(v, bf16x2c); return __builtin_bit_cast(unsigned, r); }
; #define SLOAD(i, t) do { const long rb_ = TROW(t); const char* vt_ = (const char*)Vh + rb_ * (LDK * 2); const char* kt_ = (const char*)Kh + rb_ * (LDK * 2); \
;     sr_[i].vs0 = *(const bf16x8*)(vt_ + lo0); sr_[i].vs1 = *(const bf16x8*)(vt_ + lo0 + 32 * LDK * 2); \
;     sr_[i].ks0 = *(const bf16x8*)(kt_ + lo0); sr_[i].ks1 = *(const bf16x8*)(kt_ + lo0 + 32 * LDK * 2); } while (0)
; #define SWRITE(bb, i) do { *(bf16x8*)((char*)V_lds + (bb) * SHM_V + vst0) = sr_[i].vs0;          \
;     *(bf16x8*)((char*)V_lds + (bb) * SHM_V + vst1) = sr_[i].vs1; int kc = sc * 2;               \
;     *(bf16x8*)((char*)K_lds + (bb) * SHM_K + KSWZ(sr, kc)) = sr_[i].ks0;                       \
;     *(bf16x8*)((char*)K_lds + (bb) * SHM_K + KSWZ(32 + sr, kc)) = sr_[i].ks1; } while (0)
; __device__ __forceinline__ void load_q_roped(const bf16_t* Qw, const float* __restrict__ wq, const float* __restrict__ RT, int pr, int pc, int hi, int lane, bf16x8 (&qr)[8]) {
;     ...
;       for (int e = 0; e < 8; ++e) { const float cs = t[e >> 1][(e & 1) * 2], sn = t[e >> 1][(e & 1) * 2 + 1];
;         const float x1 = y[d0][e], x2 = y[d0 + 2][e]; y[d0][e] = x1 * cs - x2 * sn; y[d0 + 2][e] = x1 * sn + x2 * cs; } }
; #pragma unroll
;   for (int d0 = 0; d0 < 8; ++d0) { u32x4 w; w.x = cvtpk(y[d0][0], y[d0][1]); w.y = cvtpk(y[d0][2], y[d0][3]); w.z = cvtpk(y[d0][4], y[d0][5]); w.w = cvtpk(y[d0][6], y[d0][7]);
;     qr[d0] = *reinterpret_cast<bf16x8*>(&w); }
; template <bool META>
; __device__ __forceinline__ void attn_unit(const bf16_t* Q, bf16_t* Oo, const bf16_t* __restrict__ Kb, const bf16_t* __restrict__ Vb, int b, int kvh, int h, int qb, char* lds, const int tid, const float* qn, const float* RT) {
;     ...
;   f32x16 pA0, pA1, pB0, pB1; float mnA, mnB, alA, alB; bf16x8 pa0, pa1, pa2, pa3;
;   constexpr int SE = 0, SO = 0;
;   SLOAD(SE, 0); asm volatile("s_waitcnt vmcnt(0)" ::: "memory"); SWRITE(0, SE); __syncthreads();
	v_pk_mul_f32 v[146:147], v[104:105], v[218:219]
	v_pk_mul_f32 v[148:149], v[102:103], v[226:227]
	v_pk_mul_f32 v[110:111], v[92:93], v[204:205]
	v_pk_mul_f32 v[114:115], v[88:89], v[248:249]
	global_load_dwordx4 v[86:89], v[86:87], off
	s_nop 0
	global_load_dwordx4 v[90:93], v[90:91], off
	v_pk_mul_f32 v[128:129], v[128:129], v[0:1] op_sel_hi:[1,0]
	global_load_dwordx4 v[102:105], v[106:107], off
	v_add_co_u32_e32 v106, vcc, s37, v106
	v_pk_mul_f32 v[120:121], v[120:121], v[0:1] op_sel_hi:[1,0]
	s_nop 0
	v_addc_co_u32_e32 v107, vcc, 0, v107, vcc
	global_load_dwordx4 v[106:109], v[106:107], off
	v_pk_mul_f32 v[2:3], v[2:3], v[0:1] op_sel_hi:[1,0]
	v_pk_mul_f32 v[128:129], v[128:129], v[140:141]
	v_pk_mul_f32 v[140:141], v[120:121], v[220:221]
	v_pk_mul_f32 v[120:121], v[2:3], v[158:159]
	v_pk_mul_f32 v[2:3], v[16:17], v[0:1] op_sel_hi:[1,0]
	v_mov_b32_e32 v17, v48
	v_mov_b32_e32 v48, v47
	v_mov_b32_e32 v16, v46
	v_pk_mul_f32 v[46:47], v[48:49], v[116:117]
	v_pk_mul_f32 v[4:5], v[4:5], v[0:1] op_sel_hi:[1,0]
	v_pk_fma_f32 v[46:47], v[16:17], v[120:121], v[46:47] neg_lo:[0,0,1] neg_hi:[0,0,1]
	v_pk_mul_f32 v[16:17], v[16:17], v[116:117]
	v_pk_mul_f32 v[4:5], v[4:5], v[156:157]
	v_pk_fma_f32 v[16:17], v[48:49], v[120:121], v[16:17]
	v_mov_b32_e32 v49, v44
	v_mov_b32_e32 v44, v43
	v_mov_b32_e32 v48, v42
	v_pk_mul_f32 v[42:43], v[44:45], v[114:115]
	v_pk_mul_f32 v[6:7], v[6:7], v[0:1] op_sel_hi:[1,0]
	v_pk_fma_f32 v[42:43], v[48:49], v[4:5], v[42:43] neg_lo:[0,0,1] neg_hi:[0,0,1]
	v_pk_mul_f32 v[48:49], v[48:49], v[114:115]
	v_pk_mul_f32 v[6:7], v[6:7], v[154:155]
	v_pk_fma_f32 v[114:115], v[44:45], v[4:5], v[48:49]
	v_mov_b32_e32 v5, v40
	v_mov_b32_e32 v40, v39
	v_mov_b32_e32 v4, v38
	v_pk_mul_f32 v[38:39], v[40:41], v[112:113]
	v_pk_mul_f32 v[8:9], v[8:9], v[0:1] op_sel_hi:[1,0]
	v_pk_fma_f32 v[38:39], v[4:5], v[6:7], v[38:39] neg_lo:[0,0,1] neg_hi:[0,0,1]
	v_pk_mul_f32 v[4:5], v[4:5], v[112:113]
	v_pk_mul_f32 v[8:9], v[8:9], v[152:153]
	v_pk_fma_f32 v[112:113], v[40:41], v[6:7], v[4:5]
	v_mov_b32_e32 v5, v32
	v_mov_b32_e32 v32, v31
	v_mov_b32_e32 v4, v30
	v_pk_mul_f32 v[6:7], v[32:33], v[110:111]
	v_pk_mul_f32 v[94:95], v[94:95], v[0:1] op_sel_hi:[1,0]
	v_pk_fma_f32 v[30:31], v[4:5], v[8:9], v[6:7] neg_lo:[0,0,1] neg_hi:[0,0,1]
	v_pk_mul_f32 v[4:5], v[4:5], v[110:111]
	v_pk_mul_f32 v[94:95], v[94:95], v[200:201]
	v_pk_mul_f32 v[10:11], v[10:11], v[0:1] op_sel_hi:[1,0]
	v_pk_fma_f32 v[110:111], v[32:33], v[8:9], v[4:5]
	v_mov_b32_e32 v5, v36
	v_mov_b32_e32 v36, v35
	v_pk_mul_f32 v[10:11], v[10:11], v[150:151]
	v_mov_b32_e32 v4, v34
	v_pk_mul_f32 v[6:7], v[36:37], v[94:95]
	v_pk_mul_f32 v[96:97], v[96:97], v[0:1] op_sel_hi:[1,0]
	v_pk_fma_f32 v[116:117], v[4:5], v[10:11], v[6:7] neg_lo:[0,0,1] neg_hi:[0,0,1]
	v_pk_mul_f32 v[4:5], v[4:5], v[94:95]
	v_pk_mul_f32 v[96:97], v[96:97], v[198:199]
	v_pk_mul_f32 v[12:13], v[12:13], v[0:1] op_sel_hi:[1,0]
	v_pk_fma_f32 v[94:95], v[36:37], v[10:11], v[4:5]
	v_mov_b32_e32 v5, v28
	v_mov_b32_e32 v28, v27
	v_pk_mul_f32 v[12:13], v[12:13], v[202:203]
	v_mov_b32_e32 v4, v26
	v_pk_mul_f32 v[6:7], v[28:29], v[96:97]
	v_pk_mul_f32 v[98:99], v[98:99], v[0:1] op_sel_hi:[1,0]
	v_pk_fma_f32 v[120:121], v[4:5], v[12:13], v[6:7] neg_lo:[0,0,1] neg_hi:[0,0,1]
	v_pk_mul_f32 v[4:5], v[4:5], v[96:97]
	v_pk_mul_f32 v[98:99], v[98:99], v[240:241]
	v_pk_mul_f32 v[82:83], v[82:83], v[0:1] op_sel_hi:[1,0]
	v_pk_fma_f32 v[12:13], v[28:29], v[12:13], v[4:5]
	v_mov_b32_e32 v5, v24
	v_mov_b32_e32 v24, v23
	v_pk_mul_f32 v[82:83], v[82:83], v[238:239]
	v_mov_b32_e32 v4, v22
	v_pk_mul_f32 v[6:7], v[24:25], v[98:99]
	v_pk_mul_f32 v[100:101], v[100:101], v[0:1] op_sel_hi:[1,0]
	v_pk_fma_f32 v[96:97], v[4:5], v[82:83], v[6:7] neg_lo:[0,0,1] neg_hi:[0,0,1]
	v_pk_mul_f32 v[4:5], v[4:5], v[98:99]
	v_pk_mul_f32 v[124:125], v[124:125], v[0:1] op_sel_hi:[1,0]
	v_pk_mul_f32 v[122:123], v[122:123], v[0:1] op_sel_hi:[1,0]
	v_pk_mul_f32 v[118:119], v[118:119], v[0:1] op_sel_hi:[1,0]
	v_pk_mul_f32 v[100:101], v[100:101], v[232:233]
	v_pk_mul_f32 v[84:85], v[84:85], v[0:1] op_sel_hi:[1,0]
	v_pk_fma_f32 v[82:83], v[24:25], v[82:83], v[4:5]
	v_mov_b32_e32 v5, v20
	v_mov_b32_e32 v20, v19
	v_add_u32_e32 v0, 0, v179
	v_pk_mul_f32 v[84:85], v[84:85], v[230:231]
	v_mov_b32_e32 v4, v18
	v_pk_mul_f32 v[6:7], v[20:21], v[100:101]
	s_waitcnt vmcnt(0)
	s_waitcnt vmcnt(3)
	ds_write_b128 v168, v[86:89]
	s_waitcnt vmcnt(2)
	ds_write_b128 v169, v[90:93]
	s_waitcnt vmcnt(1)
	ds_write_b128 v0, v[102:105] offset:49152
	v_add_u32_e32 v0, 0, v180
	v_pk_mul_f32 v[2:3], v[2:3], v[130:131]
	v_pk_fma_f32 v[130:131], v[4:5], v[84:85], v[6:7] neg_lo:[0,0,1] neg_hi:[0,0,1]
	v_pk_mul_f32 v[4:5], v[4:5], v[100:101]
	s_waitcnt vmcnt(0)
	ds_write_b128 v0, v[106:109] offset:49152
	v_add_u32_e32 v0, 0, v182
	v_pk_fma_f32 v[84:85], v[20:21], v[84:85], v[4:5]
	s_waitcnt lgkmcnt(0)
	s_barrier
; __device__ __forceinline__ unsigned cvtpk(float lo, float hi) { const f32x2c v = {lo, hi}; const bf16x2c r = __builtin_convertvector(v, bf16x2c); return __builtin_bit_cast(unsigned, r); }
; __device__ __forceinline__ void qkt(f32x16& p0, f32x16& p1, const bf16_t* Ks, const bf16x8* qr, int r32, int hi) {
;   p0 = f32x16{}; p1 = f32x16{};
; #pragma unroll
;   for (int d0 = 0; d0 < 8; ++d0) { int cb = (d0 * 16 + hi * 8) * 2;
;     bf16x8 b0 = *reinterpret_cast<const bf16x8*>((const char*)Ks + KSWZ(r32, cb));
;     bf16x8 b1 = *reinterpret_cast<const bf16x8*>((const char*)Ks + KSWZ(32 + r32, cb));
;     p0 = __builtin_amdgcn_mfma_f32_32x32x16_bf16(b0, qr[d0], p0, 0, 0, 0);
;     p1 = __builtin_amdgcn_mfma_f32_32x32x16_bf16(b1, qr[d0], p1, 0, 0, 0); }
; }
; __device__ __forceinline__ void load_q_roped(const bf16_t* Qw, const float* __restrict__ wq, const float* __restrict__ RT, int pr, int pc, int hi, int lane, bf16x8 (&qr)[8]) {
;     ...
; #pragma unroll
;   for (int d0 = 0; d0 < 8; ++d0) { u32x4 w; w.x = cvtpk(y[d0][0], y[d0][1]); w.y = cvtpk(y[d0][2], y[d0][3]); w.z = cvtpk(y[d0][4], y[d0][5]); w.w = cvtpk(y[d0][6], y[d0][7]);
;     qr[d0] = *reinterpret_cast<bf16x8*>(&w); }
	ds_read_b128 v[4:7], v0 offset:49152
	v_pk_mul_f32 v[118:119], v[118:119], v[228:229]
	v_mov_b32_e32 v9, v80
	v_mov_b32_e32 v80, v79
	v_mov_b32_e32 v8, v78
	v_pk_mul_f32 v[10:11], v[80:81], v[118:119]
	v_cvt_pk_bf16_f32 v98, v46, v47
	v_cvt_pk_bf16_f32 v99, v42, v43
	v_cvt_pk_bf16_f32 v100, v38, v39
	v_cvt_pk_bf16_f32 v101, v30, v31
	v_mov_b32_e32 v89, v76
	v_mov_b32_e32 v76, v75
	v_pk_fma_f32 v[78:79], v[8:9], v[148:149], v[10:11] neg_lo:[0,0,1] neg_hi:[0,0,1]
	v_pk_mul_f32 v[86:87], v[8:9], v[118:119]
	ds_read_b128 v[8:11], v0 offset:50176
	s_waitcnt lgkmcnt(1)
	v_mfma_f32_32x32x16_bf16 v[18:33], v[4:7], v[98:101], 0
	v_mov_b32_e32 v88, v74
	v_mul_f32_e64 v4, v76, v140
	v_mul_f32_e64 v5, v77, v141
	v_add_u32_e32 v0, 0, v182
	v_fma_f32 v74, v88, v146, -v4
	v_fma_f32 v75, v89, v147, -v5
	ds_read_b128 v[4:7], v0 offset:51200
	v_pk_mul_f32 v[122:123], v[122:123], v[216:217]
	v_mov_b32_e32 v91, v72
	v_cvt_pk_bf16_f32 v102, v116, v117
	v_cvt_pk_bf16_f32 v103, v120, v121
	v_cvt_pk_bf16_f32 v104, v96, v97
	v_cvt_pk_bf16_f32 v105, v130, v131
	v_mov_b32_e32 v72, v71
	s_waitcnt lgkmcnt(1)
	v_mfma_f32_32x32x16_bf16 v[34:49], v[8:11], v[98:101], 0
	v_mov_b32_e32 v90, v70
	ds_read_b128 v[8:11], v0 offset:52224
	v_add_u32_e32 v0, 0, v182
	v_cvt_pk_bf16_f32 v106, v16, v17
	v_cvt_pk_bf16_f32 v107, v114, v115
	v_cvt_pk_bf16_f32 v108, v112, v113
	v_cvt_pk_bf16_f32 v109, v110, v111
	s_waitcnt lgkmcnt(1)
	v_mfma_f32_32x32x16_bf16 v[18:33], v[4:7], v[102:105], v[18:33]
	v_mul_f32_e64 v4, v72, v122
	v_mul_f32_e64 v5, v73, v123
	v_cvt_pk_bf16_f32 v110, v94, v95
	v_fma_f32 v70, v90, v144, -v4
	v_fma_f32 v71, v91, v145, -v5
	ds_read_b128 v[4:7], v0 offset:53248
	v_cvt_pk_bf16_f32 v111, v12, v13
	v_cvt_pk_bf16_f32 v112, v82, v83
	v_cvt_pk_bf16_f32 v113, v84, v85
	s_waitcnt lgkmcnt(1)
	v_mfma_f32_32x32x16_bf16 v[34:49], v[8:11], v[102:105], v[34:49]
	ds_read_b128 v[8:11], v0 offset:54272
	v_add_u32_e32 v0, 0, v182
	v_mov_b32_e32 v97, v60
	v_mov_b32_e32 v60, v59
	v_mov_b32_e32 v96, v58
	v_pk_mul_f32 v[124:125], v[124:125], v[192:193]
	v_mov_b32_e32 v93, v68
	s_waitcnt lgkmcnt(1)
	v_mfma_f32_32x32x16_bf16 v[18:33], v[4:7], v[106:109], v[18:33]
	ds_read_b128 v[4:7], v0 offset:55296
	v_mov_b32_e32 v68, v67
	v_mov_b32_e32 v92, v66
	v_mul_f32_e64 v66, v68, v124
	v_mul_f32_e64 v67, v69, v125
	v_mov_b32_e32 v59, v56
	v_pk_fma_f32 v[16:17], v[92:93], v[142:143], v[66:67] neg_lo:[0,0,1] neg_hi:[0,0,1]
	v_mov_b32_e32 v56, v55
	s_waitcnt lgkmcnt(1)
	v_mfma_f32_32x32x16_bf16 v[34:49], v[8:11], v[106:109], v[34:49]
	ds_read_b128 v[8:11], v0 offset:56320
	v_add_u32_e32 v0, 0, v182
	v_cvt_pk_bf16_f32 v114, v78, v79
	v_cvt_pk_bf16_f32 v115, v74, v75
	v_cvt_pk_bf16_f32 v116, v70, v71
	v_cvt_pk_bf16_f32 v117, v16, v17
	v_mov_b32_e32 v58, v54
	s_waitcnt lgkmcnt(1)
	v_mfma_f32_32x32x16_bf16 v[18:33], v[4:7], v[110:113], v[18:33]
	v_mul_f32_e64 v4, v60, v128
	v_mul_f32_e64 v5, v61, v129
	v_mov_b32_e32 v67, v64
	v_fma_f32 v12, v96, v136, -v4
	v_fma_f32 v13, v97, v137, -v5
	ds_read_b128 v[4:7], v0 offset:57344
	v_mov_b32_e32 v64, v63
	v_mov_b32_e32 v55, v52
	v_mov_b32_e32 v52, v51
	s_waitcnt lgkmcnt(1)
	v_mfma_f32_32x32x16_bf16 v[34:49], v[8:11], v[110:113], v[34:49]
	ds_read_b128 v[8:11], v0 offset:58368
	v_add_u32_e32 v0, 0, v182
	v_mov_b32_e32 v66, v62
	v_mul_f32_e64 v62, v64, v132
	v_mul_f32_e64 v63, v65, v133
	v_mov_b32_e32 v54, v50
	v_pk_fma_f32 v[62:63], v[66:67], v[138:139], v[62:63] neg_lo:[0,0,1] neg_hi:[0,0,1]
	v_cvt_pk_bf16_f32 v119, v12, v13
	s_waitcnt lgkmcnt(1)
	v_mfma_f32_32x32x16_bf16 v[18:33], v[4:7], v[114:117], v[18:33]
	v_mul_f32_e64 v4, v56, v14
	v_mul_f32_e64 v5, v57, v15
	v_cvt_pk_bf16_f32 v118, v62, v63
	v_fma_f32 v16, v58, v134, -v4
	v_fma_f32 v17, v59, v135, -v5
	ds_read_b128 v[4:7], v0 offset:59392
	v_cvt_pk_bf16_f32 v120, v16, v17
	v_pk_fma_f32 v[12:13], v[80:81], v[148:149], v[86:87]
	v_pk_mul_f32 v[14:15], v[58:59], v[14:15]
	s_waitcnt lgkmcnt(1)
	v_mfma_f32_32x32x16_bf16 v[34:49], v[8:11], v[114:117], v[34:49]
	v_mul_f32_e64 v8, v52, v2
	v_mul_f32_e64 v9, v53, v3
	v_mul_f32_e64 v2, v54, v2
	v_mul_f32_e64 v3, v55, v3
	v_fma_f32 v8, v54, v126, -v8
	v_fma_f32 v9, v55, v127, -v9
	v_pk_fma_f32 v[2:3], v[52:53], v[126:127], v[2:3]
	v_cvt_pk_bf16_f32 v121, v8, v9
	ds_read_b128 v[8:11], v0 offset:60416
	v_add_u32_e32 v0, 0, v182
	s_waitcnt lgkmcnt(1)
	v_mfma_f32_32x32x16_bf16 v[18:33], v[4:7], v[118:121], v[18:33]
	v_mul_f32_e64 v4, v88, v140
	v_mul_f32_e64 v5, v89, v141
	v_mov_b64_e32 v[248:249], v[174:175]
	v_fma_f32 v16, v76, v146, v4
	v_fma_f32 v17, v77, v147, v5
	v_pk_mul_f32 v[4:5], v[90:91], v[122:123]
	v_cvt_pk_bf16_f32 v122, v12, v13
	v_pk_fma_f32 v[50:51], v[72:73], v[144:145], v[4:5]
	ds_read_b128 v[4:7], v0 offset:61440
	s_waitcnt lgkmcnt(1)
	v_mfma_f32_32x32x16_bf16 v[34:49], v[8:11], v[118:121], v[34:49]
	v_mul_f32_e64 v8, v92, v124
	v_mul_f32_e64 v9, v93, v125
	v_cvt_pk_bf16_f32 v123, v16, v17
	v_fma_f32 v8, v68, v142, v8
	v_fma_f32 v9, v69, v143, v9
	v_cvt_pk_bf16_f32 v124, v50, v51
	v_cvt_pk_bf16_f32 v125, v8, v9
	ds_read_b128 v[8:11], v0 offset:62464
	v_add_u32_e32 v0, 0, v182
	s_waitcnt lgkmcnt(1)
	v_mfma_f32_32x32x16_bf16 v[18:33], v[4:7], v[122:125], v[18:33]
	v_mul_f32_e64 v4, v66, v132
	v_mul_f32_e64 v5, v67, v133
	v_mov_b64_e32 v[242:243], v[244:245]
	v_fma_f32 v12, v64, v138, v4
	v_fma_f32 v13, v65, v139, v5
	v_pk_mul_f32 v[4:5], v[96:97], v[128:129]
	v_cvt_pk_bf16_f32 v126, v12, v13
	v_pk_fma_f32 v[16:17], v[60:61], v[136:137], v[4:5]
	ds_read_b128 v[4:7], v0 offset:63488
	s_waitcnt lgkmcnt(1)
; #define SLOAD(i, t) do { const long rb_ = TROW(t); const char* vt_ = (const char*)Vh + rb_ * (LDK * 2); const char* kt_ = (const char*)Kh + rb_ * (LDK * 2); \
;     sr_[i].vs0 = *(const bf16x8*)(vt_ + lo0); sr_[i].vs1 = *(const bf16x8*)(vt_ + lo0 + 32 * LDK * 2); \
;     sr_[i].ks0 = *(const bf16x8*)(kt_ + lo0); sr_[i].ks1 = *(const bf16x8*)(kt_ + lo0 + 32 * LDK * 2); } while (0)
; #define SWRITE(bb, i) do { *(bf16x8*)((char*)V_lds + (bb) * SHM_V + vst0) = sr_[i].vs0;          \
;     *(bf16x8*)((char*)V_lds + (bb) * SHM_V + vst1) = sr_[i].vs1; int kc = sc * 2;               \
;     *(bf16x8*)((char*)K_lds + (bb) * SHM_K + KSWZ(sr, kc)) = sr_[i].ks0;                       \
;     *(bf16x8*)((char*)K_lds + (bb) * SHM_K + KSWZ(32 + sr, kc)) = sr_[i].ks1; } while (0)
; #define SWAIT() asm volatile("s_waitcnt vmcnt(0)" ::: "memory")
; __device__ __forceinline__ void partialSM(f32x16& p0, f32x16& p1, float& m_reg, float& mn, float& alpha) {
;   constexpr float C = ASCALE * 1.4426950408889634f;
;   float pmax = p0[0];
; #pragma unroll
;   for (int r = 1; r < 16; ++r) pmax = fmaxf(pmax, p0[r]);
; #pragma unroll
;   for (int r = 0; r < 16; ++r) pmax = fmaxf(pmax, p1[r]);
;   { auto rr = __builtin_amdgcn_permlane32_swap(__float_as_uint(pmax), __float_as_uint(pmax), false, false);
;     pmax = fmaxf(__uint_as_float(rr[0]), __uint_as_float(rr[1])); }
;   if (__builtin_expect(__all(pmax - m_reg <= ATHR / ASCALE), 1)) { mn = m_reg; alpha = 1.f; }
;   else { mn = fmaxf(m_reg, pmax); alpha = __builtin_amdgcn_exp2f((m_reg - mn) * C); m_reg = mn; }
;   float mnC = -mn * C;
; #pragma unroll
;   for (int r = 0; r < 16; ++r) p0[r] = fmaf(p0[r], C, mnC);
; #pragma unroll
;   for (int r = 0; r < 16; ++r) p1[r] = fmaf(p1[r], C, mnC);
; #pragma unroll
;   for (int r = 0; r < 16; ++r) p0[r] = __builtin_amdgcn_exp2f(p0[r]);
; }
; template <bool META>
; __device__ __forceinline__ void attn_unit(const bf16_t* Q, bf16_t* Oo, const bf16_t* __restrict__ Kb, const bf16_t* __restrict__ Vb, int b, int kvh, int h, int qb, char* lds, const int tid, const float* qn, const float* RT) {
;     ...
;   SLOAD(SE, 0); asm volatile("s_waitcnt vmcnt(0)" ::: "memory"); SWRITE(0, SE); __syncthreads();
;   qkt(pA0, pA1, K_lds, qr, r32, hi); partialSM(pA0, pA1, m_reg, mnA, alA);
;   SLOAD(SO, 1);
;   SWAIT(); SWRITE(1, SO); __syncthreads();
;   int bc = 1;
	v_mfma_f32_32x32x16_bf16 v[34:49], v[8:11], v[122:125], v[34:49]
	v_fma_f32 v8, v56, v134, v14
	v_fma_f32 v9, v57, v135, v15
	v_cvt_pk_bf16_f32 v127, v16, v17
	v_cvt_pk_bf16_f32 v128, v8, v9
	v_cvt_pk_bf16_f32 v129, v2, v3
	ds_read_b128 v[8:11], v0 offset:64512
	v_mov_b32_e32 v245, v196
	s_waitcnt lgkmcnt(1)
	v_mfma_f32_32x32x16_bf16 v[18:33], v[4:7], v[126:129], v[18:33]
	s_waitcnt lgkmcnt(0)
	v_mfma_f32_32x32x16_bf16 v[34:49], v[8:11], v[126:129], v[34:49]
	s_nop 9
	v_max_f32_e32 v0, v19, v19
	v_max_f32_e32 v2, v18, v18
	v_max_f32_e32 v0, v2, v0
	v_max3_f32 v0, v0, v20, v21
	v_max3_f32 v0, v0, v22, v23
	v_max3_f32 v0, v0, v24, v25
	v_max3_f32 v0, v0, v26, v27
	v_max3_f32 v0, v0, v28, v29
	v_max3_f32 v0, v0, v30, v31
	v_max3_f32 v0, v0, v32, v33
	v_max3_f32 v0, v0, v34, v35
	v_max3_f32 v0, v0, v36, v37
	v_max3_f32 v0, v0, v38, v39
	v_max3_f32 v0, v0, v40, v41
	v_max3_f32 v0, v0, v42, v43
	v_max3_f32 v0, v0, v44, v45
	v_max3_f32 v0, v0, v46, v47
	v_max3_f32 v0, v0, v48, v49
	v_mov_b32_e32 v2, v0
	s_nop 1
	v_permlane32_swap_b32_e32 v0, v2
	v_max_f32_e32 v2, v2, v2
	v_max_f32_e32 v0, v0, v0
	v_max_f32_e32 v0, v0, v2
	v_add_f32_e32 v2, 0x7149f2ca, v0
	v_cmp_ge_f32_e32 vcc, s25, v2
	s_cmp_eq_u64 vcc, exec
	s_cselect_b64 vcc, -1, 0
	s_bitset1_b32 s0, 15
	s_add_u32 s6, s42, s0
	s_addc_u32 s7, s43, s1
	s_add_u32 s8, s40, s0
	v_lshl_add_u64 v[2:3], s[6:7], 0, v[166:167]
	s_addc_u32 s9, s41, s1
	v_add_co_u32_e64 v4, s[0:1], s37, v2
	v_max_f32_e32 v0, 0xf149f2ca, v0
	s_nop 0
	v_addc_co_u32_e64 v5, s[0:1], 0, v3, s[0:1]
	global_load_dwordx4 v[50:53], v[2:3], off
	global_load_dwordx4 v[54:57], v[4:5], off
	v_lshl_add_u64 v[2:3], s[8:9], 0, v[184:185]
	global_load_dwordx4 v[58:61], v[2:3], off
	v_add_co_u32_e64 v2, s[0:1], s37, v2
	v_cndmask_b32_e32 v150, v0, v246, vcc
	s_nop 0
	v_addc_co_u32_e64 v3, s[0:1], 0, v3, s[0:1]
	global_load_dwordx4 v[62:65], v[2:3], off
	v_sub_f32_e32 v2, 0xf149f2ca, v0
	v_mul_f32_e32 v2, 0x3e0293ee, v2
	v_exp_f32_e32 v66, v2
	v_mul_f32_e32 v0, 0xbe0293ee, v150
	v_fmamk_f32 v18, v18, 0x3e0293ee, v0
	v_fmamk_f32 v19, v19, 0x3e0293ee, v0
	v_cndmask_b32_e64 v192, v66, 1.0, vcc
	v_mov_b32_e32 v66, v0
	v_fmamk_f32 v20, v20, 0x3e0293ee, v0
	v_fmamk_f32 v21, v21, 0x3e0293ee, v0
	v_fmamk_f32 v22, v22, 0x3e0293ee, v0
	v_fmamk_f32 v23, v23, 0x3e0293ee, v0
	v_fmamk_f32 v24, v24, 0x3e0293ee, v0
	v_fmamk_f32 v25, v25, 0x3e0293ee, v0
	v_fmamk_f32 v26, v26, 0x3e0293ee, v0
	v_fmamk_f32 v27, v27, 0x3e0293ee, v0
	v_fmamk_f32 v28, v28, 0x3e0293ee, v0
	v_fmamk_f32 v29, v29, 0x3e0293ee, v0
	v_fmamk_f32 v30, v30, 0x3e0293ee, v0
	v_fmamk_f32 v31, v31, 0x3e0293ee, v0
	v_fmamk_f32 v32, v32, 0x3e0293ee, v0
	v_fmac_f32_e32 v66, 0x3e0293ee, v33
	s_add_i32 s0, 0, 0x10000
	s_mov_b32 s6, s5
	s_mov_b32 s7, s5
	s_mov_b32 s8, s5
	s_mov_b32 s9, s5
	v_mov_b64_e32 v[2:3], s[4:5]
	v_pk_fma_f32 v[130:131], v[48:49], s[36:37], v[0:1] op_sel_hi:[1,0,0]
	v_pk_fma_f32 v[132:133], v[46:47], s[36:37], v[0:1] op_sel_hi:[1,0,0]
	v_pk_fma_f32 v[134:135], v[44:45], s[36:37], v[0:1] op_sel_hi:[1,0,0]
	v_pk_fma_f32 v[136:137], v[42:43], s[36:37], v[0:1] op_sel_hi:[1,0,0]
	v_pk_fma_f32 v[138:139], v[40:41], s[36:37], v[0:1] op_sel_hi:[1,0,0]
	v_pk_fma_f32 v[140:141], v[38:39], s[36:37], v[0:1] op_sel_hi:[1,0,0]
	v_pk_fma_f32 v[142:143], v[36:37], s[36:37], v[0:1] op_sel_hi:[1,0,0]
	v_pk_fma_f32 v[144:145], v[34:35], s[36:37], v[0:1] op_sel_hi:[1,0,0]
	v_exp_f32_e32 v146, v18
	v_exp_f32_e32 v147, v19
	v_exp_f32_e32 v148, v20
	v_exp_f32_e32 v159, v21
	v_exp_f32_e32 v160, v22
	v_exp_f32_e32 v209, v23
	v_exp_f32_e32 v149, v24
	v_exp_f32_e32 v161, v25
	v_exp_f32_e32 v151, v26
	v_exp_f32_e32 v153, v27
	v_exp_f32_e32 v154, v28
	v_exp_f32_e32 v157, v29
	v_exp_f32_e32 v152, v30
	v_exp_f32_e32 v155, v31
	v_exp_f32_e32 v156, v32
	v_exp_f32_e32 v158, v66
	v_add_u32_e32 v0, s0, v179
	v_mov_b64_e32 v[16:17], s[18:19]
	s_waitcnt vmcnt(0)
	s_waitcnt vmcnt(3)
	ds_write_b128 v168, v[50:53] offset:16384
	s_waitcnt vmcnt(2)
	ds_write_b128 v169, v[54:57] offset:16384
	v_mov_b64_e32 v[4:5], s[6:7]
	s_waitcnt vmcnt(1)
	ds_write_b128 v0, v[58:61]
	v_add_u32_e32 v0, s0, v180
	v_mov_b64_e32 v[6:7], s[8:9]
	v_mov_b64_e32 v[8:9], s[10:11]
	v_mov_b64_e32 v[10:11], s[12:13]
	v_mov_b64_e32 v[12:13], s[14:15]
	v_mov_b64_e32 v[14:15], s[16:17]
	s_waitcnt vmcnt(0)
	ds_write_b128 v0, v[62:65]
	v_mov_b64_e32 v[64:65], v[16:17]
	v_mov_b64_e32 v[48:49], v[16:17]
	v_mov_b64_e32 v[32:33], v[16:17]
	v_lshl_add_u64 v[168:169], s[42:43], 0, v[166:167]
	s_mov_b64 s[12:13], s[42:43]
	s_mov_b64 s[14:15], s[40:41]
	v_lshrrev_b32_e32 v239, 6, v208
	s_nop 0
	v_readfirstlane_b32 s18, v239
	s_lshl_b32 s18, s18, 11
	v_add_u32_e32 v238, 0x4000, v166
	s_bitset1_b32 s90, 7
	v_mov_b32_e32 v0, 0
	s_mov_b32 s4, -1
	v_mov_b64_e32 v[62:63], v[14:15]
	v_mov_b64_e32 v[60:61], v[12:13]
	v_mov_b64_e32 v[58:59], v[10:11]
	v_mov_b64_e32 v[56:57], v[8:9]
	v_mov_b64_e32 v[54:55], v[6:7]
	v_mov_b64_e32 v[52:53], v[4:5]
	v_mov_b64_e32 v[50:51], v[2:3]
	v_mov_b64_e32 v[46:47], v[14:15]
	v_mov_b64_e32 v[44:45], v[12:13]
	v_mov_b64_e32 v[42:43], v[10:11]
	v_mov_b64_e32 v[40:41], v[8:9]
	v_mov_b64_e32 v[38:39], v[6:7]
	v_mov_b64_e32 v[36:37], v[4:5]
	v_mov_b64_e32 v[34:35], v[2:3]
	v_mov_b64_e32 v[30:31], v[14:15]
	v_mov_b64_e32 v[28:29], v[12:13]
	v_mov_b64_e32 v[26:27], v[10:11]
	v_mov_b64_e32 v[24:25], v[8:9]
	v_mov_b64_e32 v[22:23], v[6:7]
	v_mov_b64_e32 v[20:21], v[4:5]
	v_mov_b64_e32 v[18:19], v[2:3]
	s_waitcnt lgkmcnt(0)
	s_barrier
	.p2align	6
